# RWKV scanner loop head additionally placed at the start of a 64-byte line (p2align); GEMM K-loop heads at offsets 16/32 as before
# baseline (speedup 1.0000x reference)
; template <int CH>
; __device__ __forceinline__ void scan_unit(const Args& a, int l, int unit, unsigned char* lds) {
;     ...
;     const int lane = tid & 63, wave = tid >> 6;
;     const bool sample = unit >= 128; const int bh = (unit & 127) >> 2, rg = unit & 3, b = bh >> 2, h = bh & 3;
;     const int Tn = sample ? TS : T, rowbase = sample ? MP + b * TS : b * T, nch = Tn / CH;
;     const unsigned char* rec0 = ws_l + WS_SIN + ((size_t)rowbase * 4 + (size_t)h * Tn) * REC;
;     float* YS = (float*)(ws_l + WS_YS);
;     const bool loader = wave >= 4;
;     const int lt = tid - 256, lstep = lt >> 4, ljq = lt & 15;
;     const int rowl = lane >> 4, jq = lane & 15, vrow = rg * 16 + wave * 4 + rowl;
;     f32x2v S01 = {0.f, 0.f}, S23 = {0.f, 0.f};
;     if (!loader && sample) { const f32x4 s = *(const f32x4*)(in_I_SWKV + ((size_t)((l * NB + b) * 4 + h) * 64 + vrow) * 64 + 4 * jq); S01 = s.lo; S23 = s.hi; }
.LBB0_673:
	s_and_b64 vcc, exec, s[4:5]
	s_cbranch_vccz .LBB0_662
	v_readlane_b32 s4, v253, 2
	v_mov_b32_e32 v4, v172
	v_readlane_b32 s5, v253, 3
	s_waitcnt lgkmcnt(0)
	s_load_dwordx4 s[56:59], s[4:5], 0xe0
	s_waitcnt vmcnt(0)
	v_ashrrev_i32_e32 v0, 6, v4
	v_and_b32_e32 v16, 15, v4
	s_lshr_b32 s61, s84, 3
	s_bfe_u32 s46, s49, 0x30004
	s_lshr_b32 s48, s84, 5
	v_cmp_gt_i32_e64 s[10:11], 4, v0
	v_bfe_u32 v97, v4, 4, 2
	v_lshlrev_b32_e32 v99, 2, v0
	v_lshlrev_b32_e32 v88, 4, v16
	s_and_saveexec_b64 s[4:5], s[10:11]
	s_xor_b64 s[8:9], exec, s[4:5]
	s_cbranch_execz .LBB0_678
	s_and_b32 s0, s48, 3
	s_and_b32 s4, s61, 3
	v_or_b32_e32 v0, v99, v97
	s_lshl_b32 s0, s0, 8
	s_lshl_b32 s4, s4, 4
	v_lshlrev_b32_e32 v2, 2, v0
	v_lshlrev_b32_e32 v0, 10, v16
	v_lshl_or_b32 v140, s46, 22, v0
	v_add3_u32 v0, s4, v99, v97
	s_waitcnt lgkmcnt(0)
	s_add_u32 s4, s58, s0
	v_ashrrev_i32_e32 v1, 31, v0
	s_addc_u32 s5, s59, 0
	v_lshl_add_u64 v[90:91], v[0:1], 2, s[4:5]
	v_mov_b32_e32 v0, 0
	s_mov_b32 s78, s22
	v_cmp_eq_u32_e64 s[12:13], 15, v16
	v_cmp_eq_u32_e64 s[14:15], 14, v16
	v_cmp_eq_u32_e64 s[16:17], 0, v16
	v_cmp_eq_u32_e64 s[18:19], 1, v16
	v_cmp_eq_u32_e64 s[20:21], 2, v16
	v_cmp_eq_u32_e64 s[22:23], 3, v16
	v_cmp_eq_u32_e64 s[24:25], 4, v16
	v_cmp_eq_u32_e64 s[26:27], 5, v16
	v_cmp_eq_u32_e64 s[28:29], 6, v16
	v_cmp_eq_u32_e64 s[30:31], 7, v16
	v_cmp_eq_u32_e64 s[34:35], 8, v16
	v_cmp_eq_u32_e64 s[36:37], 9, v16
	v_cmp_eq_u32_e64 s[38:39], 10, v16
	v_cmp_eq_u32_e64 s[40:41], 11, v16
	v_cmp_eq_u32_e64 s[42:43], 12, v16
	v_cmp_eq_u32_e64 s[44:45], 13, v16
	v_or_b32_e32 v92, 0x8000, v140
	v_mov_b32_e32 v93, v141
	s_mov_b32 s4, -2
	v_add_u32_e32 v89, 0, v88
	v_add_u32_e32 v101, 0, v2
	v_mov_b32_e32 v1, v0
	v_mov_b32_e32 v2, v0
	v_mov_b32_e32 v3, v0
	s_barrier
	v_lshrrev_b32_e32 v105, 4, v89
	v_and_b32_e32 v104, 3, v105
	v_lshrrev_b32_e32 v79, 2, v105
	v_lshl_or_b32 v79, v104, 2, v79
	v_sub_u32_e32 v79, v79, v105
	v_lshlrev_b32_e32 v79, 10, v79
	v_add_u32_e32 v104, v79, v140
	v_mov_b32_e32 v105, 0
	v_lshl_add_u64 v[90:91], v[90:91], 0, v[104:105]
	v_add_u32_e32 v98, 0xa800, v89
	v_add_co_u32_e32 v90, vcc, 0x1c3e0800, v90
	v_add_u32_e32 v100, 0xa800, v101
	s_mov_b32 s4, 0
	v_addc_co_u32_e32 v91, vcc, 0, v91, vcc
	s_mov_b64 s[6:7], 0x4000
	v_bfe_u32 v105, v89, 4, 2
	v_cmp_eq_u32_e64 s[16:17], 0, v105
	v_cmp_eq_u32_e64 s[18:19], 1, v105
	v_cmp_eq_u32_e64 s[20:21], 2, v105
	v_cmp_eq_u32_e64 s[22:23], 3, v105
	ds_read_b128 v[54:57], v89
	ds_read_b128 v[6:9], v89 offset:768
	ds_read_b128 v[22:25], v89 offset:1024
	ds_read_b128 v[38:41], v89 offset:256
	ds_read_b128 v[70:73], v89 offset:512
	ds_read_b32 v78, v101 offset:1280
	ds_read_b128 v[58:61], v89 offset:1344
	ds_read_b128 v[10:13], v89 offset:2112
	ds_read_b128 v[26:29], v89 offset:2368
	ds_read_b128 v[42:45], v89 offset:1600
	ds_read_b128 v[74:77], v89 offset:1856
	ds_read_b32 v80, v101 offset:2624
	v_mov_b32_e32 v66, 0
	v_mov_b32_e32 v67, 0
	v_mov_b32_e32 v68, 0
	v_mov_b32_e32 v69, 0
	v_mov_b32_e32 v96, 0
	v_mov_b32_e32 v79, 0
	v_mov_b32_e32 v95, 0
	v_mov_b32_e32 v104, 0
	v_mov_b32_e32 v105, 0
	s_setprio 3
	.p2align 6
